# attention: waves 4-7 barrier moved between QK and softmax (half-step stagger), V tiles one ahead
# speedup vs baseline: 1.1716x; 1.1716x over previous
; __device__ __forceinline__ void attn_unit(int bh, int qb, const bf16_t* Q, const bf16_t* KN, const bf16_t* KPE, const bf16_t* VT, const float* COS, const float* SIN, bf16_t* O, LAS unsigned char* lds, int wv) {
;     int tid_; asm volatile("v_mbcnt_lo_u32_b32 %0, -1, 0\n\tv_mbcnt_hi_u32_b32 %0, -1, %0" : "=v"(tid_)); tid_ |= (wv << 6); const int tid = tid_, lane = tid & 63, wid = __builtin_amdgcn_readfirstlane(tid >> 6), r32 = lane & 31, hi = lane >> 5;
;     const int b = bh >> 4, h = bh & 15, q0 = qb * 256;
;     const size_t rowbase = (size_t)b * 2048;
;     const int qrow = q0 + 32 * wid + r32;
;     const unsigned lds0 = (unsigned)(uintptr_t)lds;
;     const bf16_t* csrc[6]; int cstep[6]; unsigned cdst[6];
; #pragma unroll
;     for (int i = 0; i < 6; ++i) { int id = wid + 8 * i; if (id > 44) id = 44;
;         if (id < 25) { const int c = id * 1024 + 16 * lane, row = c / AK_PITCH, col = c % AK_PITCH;
;             if (col < 256) { csrc[i] = KN + (rowbase + row) * 2048 + h * 128 + (col >> 1); cstep[i] = 64 * 2048; }
;             else if (col < 384) { csrc[i] = KPE + (rowbase + row) * 64 + ((col - 256) >> 1); cstep[i] = 64 * 64; }
;             else { csrc[i] = KN + (rowbase + row) * 2048 + h * 128; cstep[i] = 64 * 2048; }
;             cdst[i] = (unsigned)(id * 1024); }
;         else { const int c = (id - 25) * 1024 + 16 * lane, row = c / AV_PITCH, col = c % AV_PITCH;
;             csrc[i] = VT + (rowbase + row) * 2048 + h * 128 + (col < 256 ? (col >> 1) : 0); cstep[i] = 64 * 2048;
;             cdst[i] = (unsigned)(3 * AK_BYTES + (id - 25) * 1024); } }
;     const int NT = (q0 + 256) / 64;
;     ...
;     ATT_ISSUE(0, 0); ATT_ISSUE(1, 1);
;     bf16x8 qf[12];
;     { const bf16_t* qp = Q + (rowbase + qrow) * 3072 + h * 192 + 8 * hi;
; #pragma unroll
;       for (int d0 = 0; d0 < 12; ++d0) qf[d0] = *(const bf16x8*)(qp + 16 * d0);
; #pragma unroll
;       for (int e = 0; e < 2; ++e) { const int i0 = 16 * e + 8 * hi; const float* cp = COS + (rowbase + qrow) * 32 + i0; const float* sp = SIN + (rowbase + qrow) * 32 + i0;
;           const f32x4 c0 = *(const f32x4*)cp, c1 = *(const f32x4*)(cp + 4), s0 = *(const f32x4*)sp, s1 = *(const f32x4*)(sp + 4);
;           const u32x4 x1 = __builtin_bit_cast(u32x4, qf[8 + e]), x2 = __builtin_bit_cast(u32x4, qf[10 + e]); u32x4 n1, n2;
.LBB0_646:
	s_add_i32 s28, s54, 0
	s_mov_b32 s29, m0
	s_mov_b32 m0, s28
	s_nop 0
	global_load_lds_dwordx4 v[10:11], off
	s_mov_b32 m0, s29
	s_add_i32 s29, s55, 0
	s_mov_b32 s31, m0
	s_mov_b32 m0, s29
	s_nop 0
	global_load_lds_dwordx4 v[14:15], off
	s_mov_b32 m0, s31
	s_lshl_b32 s23, s50, 8
	s_add_i32 s31, s56, 0
	s_mov_b32 s50, m0
	s_mov_b32 m0, s31
	s_nop 0
	global_load_lds_dwordx4 v[18:19], off
	s_mov_b32 m0, s50
	s_add_i32 s50, s58, 0
	s_mov_b32 s51, m0
	s_mov_b32 m0, s50
	s_nop 0
	global_load_lds_dwordx4 v[22:23], off
	s_mov_b32 m0, s51
	s_lshl_b32 s22, s49, 5
	s_add_i32 s51, s59, 0
	s_mov_b32 s52, m0
	s_mov_b32 m0, s51
	s_nop 0
	global_load_lds_dwordx4 v[26:27], off
	s_mov_b32 m0, s52
	s_add_i32 s57, s22, s23
	s_add_i32 s25, s23, 0x100
	s_add_i32 s52, s60, 0
	s_add_i32 s64, 0, 0x5000
	s_add_i32 s65, 0, 0x6400
	s_mov_b32 s62, m0
	s_mov_b32 m0, s52
	s_nop 0
	global_load_lds_dwordx4 v[30:31], off
	s_mov_b32 m0, s62
	s_and_b64 s[62:63], s[6:7], exec
	s_cselect_b32 s62, s65, s64
	s_add_i32 s54, s54, s62
	v_lshlrev_b64 v[162:163], 1, v[12:13]
	s_and_b64 s[62:63], exec, s[16:17]
	v_lshl_add_u64 v[2:3], v[10:11], 0, v[162:163]
	s_mov_b32 s62, m0
	s_mov_b32 m0, s54
	s_nop 0
	global_load_lds_dwordx4 v[2:3], off
	s_mov_b32 m0, s62
	s_cselect_b32 s54, s65, s64
	s_add_i32 s54, s55, s54
	v_lshlrev_b64 v[164:165], 1, v[16:17]
	v_lshl_add_u64 v[2:3], v[14:15], 0, v[164:165]
	s_mov_b32 s55, m0
	s_mov_b32 m0, s54
	s_nop 0
	global_load_lds_dwordx4 v[2:3], off
	s_mov_b32 m0, s55
	s_and_b64 s[54:55], exec, s[18:19]
	s_cselect_b32 s54, s65, s64
	s_add_i32 s54, s56, s54
	v_lshlrev_b64 v[166:167], 1, v[20:21]
	v_lshl_add_u64 v[2:3], v[18:19], 0, v[166:167]
	s_mov_b32 s55, m0
	s_mov_b32 m0, s54
	s_nop 0
	global_load_lds_dwordx4 v[2:3], off
	s_mov_b32 m0, s55
	s_and_b64 s[54:55], exec, s[20:21]
	s_cselect_b32 s54, s65, s64
	s_add_i32 s54, s58, s54
	v_lshlrev_b64 v[168:169], 1, v[24:25]
	v_and_b32_e32 v190, 31, v188
	v_lshl_add_u64 v[2:3], v[22:23], 0, v[168:169]
	s_mov_b32 s55, m0
	s_mov_b32 m0, s54
	s_nop 0
	global_load_lds_dwordx4 v[2:3], off
	s_mov_b32 m0, s55
	s_and_b64 s[54:55], exec, s[26:27]
	v_lshlrev_b64 v[170:171], 1, v[28:29]
	v_or_b32_e32 v160, s57, v190
	s_cselect_b32 s54, s65, s64
	v_lshl_add_u64 v[2:3], v[26:27], 0, v[170:171]
	v_lshlrev_b64 v[172:173], 1, v[32:33]
	s_add_i32 s54, s59, s54
	s_mov_b32 s55, m0
	s_mov_b32 m0, s54
	s_nop 0
	global_load_lds_dwordx4 v[2:3], off
	s_mov_b32 m0, s55
	v_lshl_add_u64 v[2:3], v[30:31], 0, v[172:173]
	v_ashrrev_i32_e32 v161, 31, v160
	s_add_i32 s54, s60, s61
	s_mov_b32 s55, m0
	s_mov_b32 m0, s54
	s_nop 0
	global_load_lds_dwordx4 v[2:3], off
	s_mov_b32 m0, s55
	v_lshl_add_u64 v[2:3], v[160:161], 0, s[2:3]
	v_mov_b64_e32 v[4:5], s[4:5]
	v_mad_u64_u32 v[4:5], s[54:55], v2, s46, v[4:5]
	v_lshrrev_b32_e32 v80, 5, v189
	v_mad_i32_i24 v5, v3, s46, v5
	s_mul_i32 s54, s53, 0x180
	s_mov_b32 s55, s3
	v_lshl_add_u64 v[4:5], v[4:5], 0, s[54:55]
	v_lshlrev_b32_e32 v0, 4, v80
	v_lshl_add_u64 v[6:7], v[4:5], 0, v[0:1]
	v_lshlrev_b64 v[2:3], 7, v[2:3]
	global_load_dwordx4 v[34:37], v[6:7], off offset:256
	global_load_dwordx4 v[38:41], v[6:7], off offset:320
	v_lshl_add_u64 v[4:5], s[12:13], 0, v[2:3]
	v_lshl_add_u64 v[2:3], s[14:15], 0, v[2:3]
	v_and_b32_e32 v8, 32, v189
	v_mov_b32_e32 v9, v1
	v_lshl_add_u64 v[70:71], v[2:3], 0, v[8:9]
	v_lshl_add_u64 v[62:63], v[4:5], 0, v[8:9]
	global_load_dwordx4 v[42:45], v[70:71], off
	global_load_dwordx4 v[46:49], v[62:63], off
	global_load_dwordx4 v[50:53], v[70:71], off offset:16
	global_load_dwordx4 v[54:57], v[62:63], off offset:16
	global_load_dwordx4 v[112:115], v[6:7], off
	global_load_dwordx4 v[116:119], v[6:7], off offset:32
	global_load_dwordx4 v[120:123], v[6:7], off offset:64
	global_load_dwordx4 v[124:127], v[6:7], off offset:96
	global_load_dwordx4 v[128:131], v[6:7], off offset:128
	global_load_dwordx4 v[132:135], v[6:7], off offset:160
	global_load_dwordx4 v[136:139], v[6:7], off offset:192
	global_load_dwordx4 v[140:143], v[6:7], off offset:224
	global_load_dwordx4 v[2:5], v[6:7], off offset:288
	s_nop 0
	global_load_dwordx4 v[6:9], v[6:7], off offset:352
	s_nop 0
	global_load_dwordx4 v[58:61], v[62:63], off offset:80
	s_nop 0
	global_load_dwordx4 v[62:65], v[62:63], off offset:64
	s_nop 0
	global_load_dwordx4 v[66:69], v[70:71], off offset:80
	s_nop 0
	global_load_dwordx4 v[70:73], v[70:71], off offset:64
	s_lshr_b32 s54, s25, 6
	s_or_b32 s55, s57, 31
	s_add_i32 s56, s54, -4
	s_and_b64 s[6:7], s[6:7], exec
	v_lshlrev_b32_e32 v192, 2, v80
	s_cselect_b32 s58, s45, 0x5000
	s_and_b64 s[6:7], exec, s[16:17]
	s_cselect_b32 s59, s45, 0x5000
	s_and_b64 s[6:7], exec, s[18:19]
	s_waitcnt vmcnt(0)
	s_barrier
; #define ATT_ISSUE(tt, slot) do { _Pragma("unroll") for (int i_ = 0; i_ < 6; ++i_) { \
;         const unsigned dst_ = lds0 + cdst[i_] + (unsigned)(slot) * (unsigned)((wid + 8 * i_ < 25) ? AK_BYTES : AV_BYTES); \
;         att_glds16(csrc[i_] + (size_t)(tt) * cstep[i_], (unsigned)__builtin_amdgcn_readfirstlane(dst_)); } } while (0)
; #define ROPE2(W1, W2, O1, O2, CA, SA, CB, SB) { const float a1 = bf_lo(W1), a2 = bf_lo(W2), b1 = bf_hi(W1), b2 = bf_hi(W2); \
;               O1 = cvt_pk_bf16(a1 * (CA) - a2 * (SA), b1 * (CB) - b2 * (SB)); O2 = cvt_pk_bf16(a2 * (CA) + a1 * (SA), b2 * (CB) + b1 * (SB)); }
; __device__ __forceinline__ void attn_unit(int bh, int qb, const bf16_t* Q, const bf16_t* KN, const bf16_t* KPE, const bf16_t* VT, const float* COS, const float* SIN, bf16_t* O, LAS unsigned char* lds, int wv) {
;     ...
;     ATT_ISSUE(0, 0); ATT_ISSUE(1, 1);
;     bf16x8 qf[12];
;     { const bf16_t* qp = Q + (rowbase + qrow) * 3072 + h * 192 + 8 * hi;
; #pragma unroll
;       for (int d0 = 0; d0 < 12; ++d0) qf[d0] = *(const bf16x8*)(qp + 16 * d0);
; #pragma unroll
;       for (int e = 0; e < 2; ++e) { const int i0 = 16 * e + 8 * hi; const float* cp = COS + (rowbase + qrow) * 32 + i0; const float* sp = SIN + (rowbase + qrow) * 32 + i0;
;           const f32x4 c0 = *(const f32x4*)cp, c1 = *(const f32x4*)(cp + 4), s0 = *(const f32x4*)sp, s1 = *(const f32x4*)(sp + 4);
;           const u32x4 x1 = __builtin_bit_cast(u32x4, qf[8 + e]), x2 = __builtin_bit_cast(u32x4, qf[10 + e]); u32x4 n1, n2;
;     ...
;           ROPE2(x1.x, x2.x, n1.x, n2.x, c0[0], s0[0], c0[1], s0[1]); ROPE2(x1.y, x2.y, n1.y, n2.y, c0[2], s0[2], c0[3], s0[3]);
;           ROPE2(x1.z, x2.z, n1.z, n2.z, c1[0], s1[0], c1[1], s1[1]); ROPE2(x1.w, x2.w, n1.w, n2.w, c1[2], s1[2], c1[3], s1[3]);
;     ...
;           qf[8 + e] = __builtin_bit_cast(bf16x8, n1); qf[10 + e] = __builtin_bit_cast(bf16x8, n2); } }
	s_cselect_b32 s18, s45, 0x5000
	s_and_b64 s[6:7], exec, s[20:21]
	v_lshl_add_u64 v[182:183], v[16:17], 2, v[14:15]
	v_mov_b32_e32 v14, v1
	v_mov_b32_e32 v15, v1
	s_cselect_b32 s19, s45, 0x5000
	s_and_b64 s[6:7], exec, s[26:27]
	v_lshl_add_u64 v[174:175], v[32:33], 1, v[30:31]
	v_lshl_add_u64 v[176:177], v[28:29], 1, v[26:27]
	v_lshl_add_u64 v[178:179], v[24:25], 1, v[22:23]
	v_lshl_add_u64 v[180:181], v[20:21], 2, v[18:19]
	v_lshl_add_u64 v[184:185], v[12:13], 2, v[10:11]
	v_mov_b32_e32 v10, v1
	v_mov_b32_e32 v11, v1
	v_mov_b32_e32 v12, v1
	v_mov_b32_e32 v13, v1
	s_mov_b32 s53, 1
	v_lshlrev_b32_e32 v161, 3, v80
	s_mov_b32 s57, 2
	s_cselect_b32 s20, s45, 0x5000
	s_mov_b32 s21, 0
	v_mov_b32_e32 v195, 0xf149f2ca
	v_mov_b32_e32 v194, 0
	s_mov_b32 s6, 0
	s_mov_b32 s26, 0
	s_waitcnt vmcnt(0)
	v_lshlrev_b32_e32 v75, 16, v34
	v_lshlrev_b32_e32 v74, 16, v38
	v_mov_b32_e32 v76, v42
	v_mov_b32_e32 v77, v46
	v_mov_b32_e32 v78, v46
	v_mov_b32_e32 v79, v42
	v_pk_mul_f32 v[76:77], v[76:77], v[74:75]
	v_pk_mul_f32 v[74:75], v[78:79], v[74:75]
	v_mov_b32_e32 v46, v43
	v_add_f32_e32 v78, v74, v75
	v_and_b32_e32 v75, 0xffff0000, v34
	v_and_b32_e32 v74, 0xffff0000, v38
	v_sub_f32_e32 v81, v77, v76
	v_pk_mul_f32 v[76:77], v[46:47], v[74:75]
	v_mov_b32_e32 v42, v47
	v_sub_f32_e32 v34, v77, v76
	v_pk_mul_f32 v[42:43], v[42:43], v[74:75]
	v_cvt_pk_bf16_f32 v144, v81, v34
	v_mov_b32_e32 v46, v44
	v_add_f32_e32 v34, v42, v43
	v_lshlrev_b32_e32 v43, 16, v35
	v_lshlrev_b32_e32 v42, 16, v39
	v_mov_b32_e32 v47, v48
	v_pk_mul_f32 v[46:47], v[46:47], v[42:43]
	v_cvt_pk_bf16_f32 v148, v78, v34
	v_and_b32_e32 v35, 0xffff0000, v35
	v_sub_f32_e32 v74, v47, v46
	v_mov_b32_e32 v46, v48
	v_mov_b32_e32 v47, v44
	v_and_b32_e32 v34, 0xffff0000, v39
	v_mov_b32_e32 v48, v45
	v_mov_b32_e32 v44, v49
	v_pk_mul_f32 v[38:39], v[48:49], v[34:35]
	v_pk_mul_f32 v[34:35], v[44:45], v[34:35]
	v_pk_mul_f32 v[42:43], v[46:47], v[42:43]
	v_sub_f32_e32 v38, v39, v38
	v_add_f32_e32 v34, v34, v35
	v_add_f32_e32 v42, v42, v43
	v_cvt_pk_bf16_f32 v145, v74, v38
	v_cvt_pk_bf16_f32 v149, v42, v34
	v_lshlrev_b32_e32 v35, 16, v36
	v_lshlrev_b32_e32 v34, 16, v40
	v_mov_b32_e32 v38, v50
	v_mov_b32_e32 v39, v54
	v_pk_mul_f32 v[38:39], v[38:39], v[34:35]
	s_nop 0
	v_sub_f32_e32 v42, v39, v38
	v_mov_b32_e32 v38, v54
	v_mov_b32_e32 v39, v50
	v_pk_mul_f32 v[34:35], v[38:39], v[34:35]
	v_mov_b32_e32 v54, v51
	v_add_f32_e32 v43, v34, v35
	v_and_b32_e32 v35, 0xffff0000, v36
	v_and_b32_e32 v34, 0xffff0000, v40
	v_mov_b32_e32 v50, v55
	v_pk_mul_f32 v[38:39], v[54:55], v[34:35]
	v_pk_mul_f32 v[34:35], v[50:51], v[34:35]
	v_sub_f32_e32 v36, v39, v38
	v_add_f32_e32 v34, v34, v35
	v_cvt_pk_bf16_f32 v150, v43, v34
	v_lshlrev_b32_e32 v35, 16, v37
	v_lshlrev_b32_e32 v34, 16, v41
	v_mov_b32_e32 v38, v52
	v_mov_b32_e32 v39, v56
	v_pk_mul_f32 v[38:39], v[38:39], v[34:35]
	v_cvt_pk_bf16_f32 v146, v42, v36
	s_nop 0
	v_sub_f32_e32 v40, v39, v38
	v_mov_b32_e32 v38, v56
	v_mov_b32_e32 v39, v52
	v_pk_mul_f32 v[34:35], v[38:39], v[34:35]
	v_mov_b32_e32 v56, v53
	v_add_f32_e32 v38, v34, v35
	v_and_b32_e32 v35, 0xffff0000, v37
	v_and_b32_e32 v34, 0xffff0000, v41
	v_mov_b32_e32 v52, v57
	v_pk_mul_f32 v[36:37], v[56:57], v[34:35]
	v_pk_mul_f32 v[34:35], v[52:53], v[34:35]
	v_sub_f32_e32 v36, v37, v36
	v_add_f32_e32 v34, v34, v35
	v_cvt_pk_bf16_f32 v147, v40, v36
	v_cvt_pk_bf16_f32 v151, v38, v34
	v_lshlrev_b32_e32 v35, 16, v2
	v_lshlrev_b32_e32 v34, 16, v6
	v_mov_b32_e32 v36, v70
	v_mov_b32_e32 v37, v62
	v_pk_mul_f32 v[36:37], v[36:37], v[34:35]
	s_nop 0
	v_sub_f32_e32 v38, v37, v36
	v_mov_b32_e32 v36, v62
	v_mov_b32_e32 v37, v70
	v_pk_mul_f32 v[34:35], v[36:37], v[34:35]
	v_mov_b32_e32 v62, v71
	v_add_f32_e32 v39, v34, v35
	v_and_b32_e32 v35, 0xffff0000, v2
	v_and_b32_e32 v34, 0xffff0000, v6
	v_pk_mul_f32 v[36:37], v[62:63], v[34:35]
	v_mov_b32_e32 v70, v63
	v_sub_f32_e32 v2, v37, v36
	v_pk_mul_f32 v[34:35], v[70:71], v[34:35]
	v_cvt_pk_bf16_f32 v152, v38, v2
	v_mov_b32_e32 v36, v72
	v_add_f32_e32 v2, v34, v35
	v_lshlrev_b32_e32 v35, 16, v3
	v_lshlrev_b32_e32 v34, 16, v7
	v_mov_b32_e32 v37, v64
	v_pk_mul_f32 v[36:37], v[36:37], v[34:35]
	v_cvt_pk_bf16_f32 v156, v39, v2
	v_and_b32_e32 v3, 0xffff0000, v3
	v_sub_f32_e32 v38, v37, v36
	v_mov_b32_e32 v36, v64
	v_mov_b32_e32 v37, v72
	v_and_b32_e32 v2, 0xffff0000, v7
; #define LAS __attribute__((address_space(3)))
; #define ATT_ISSUE(tt, slot) do { _Pragma("unroll") for (int i_ = 0; i_ < 6; ++i_) { \
;         const unsigned dst_ = lds0 + cdst[i_] + (unsigned)(slot) * (unsigned)((wid + 8 * i_ < 25) ? AK_BYTES : AV_BYTES); \
;         att_glds16(csrc[i_] + (size_t)(tt) * cstep[i_], (unsigned)__builtin_amdgcn_readfirstlane(dst_)); } } while (0)
; #define ROPE2(W1, W2, O1, O2, CA, SA, CB, SB) { const float a1 = bf_lo(W1), a2 = bf_lo(W2), b1 = bf_hi(W1), b2 = bf_hi(W2); \
;               O1 = cvt_pk_bf16(a1 * (CA) - a2 * (SA), b1 * (CB) - b2 * (SB)); O2 = cvt_pk_bf16(a2 * (CA) + a1 * (SA), b2 * (CB) + b1 * (SB)); }
; __device__ __forceinline__ void attn_unit(int bh, int qb, const bf16_t* Q, const bf16_t* KN, const bf16_t* KPE, const bf16_t* VT, const float* COS, const float* SIN, bf16_t* O, LAS unsigned char* lds, int wv) {
;     ...
;           ROPE2(x1.x, x2.x, n1.x, n2.x, c0[0], s0[0], c0[1], s0[1]); ROPE2(x1.y, x2.y, n1.y, n2.y, c0[2], s0[2], c0[3], s0[3]);
;           ROPE2(x1.z, x2.z, n1.z, n2.z, c1[0], s1[0], c1[1], s1[1]); ROPE2(x1.w, x2.w, n1.w, n2.w, c1[2], s1[2], c1[3], s1[3]);
;     ...
;           qf[8 + e] = __builtin_bit_cast(bf16x8, n1); qf[10 + e] = __builtin_bit_cast(bf16x8, n2); } }
;     asm volatile("s_waitcnt vmcnt(0)\n\ts_barrier" ::: "memory");
;     f32x16 o[4];
; #pragma unroll
;     for (int d0 = 0; d0 < 4; ++d0)
; #pragma unroll
;         for (int r = 0; r < 16; ++r) o[d0][r] = 0.f;
;     float m_run = -1e30f, l_run = 0.f;
;     int s0i = 0, s1i = 1, s2 = 2;
;     for (int t = 0; t < NT; ++t) {
;         const bool more2 = t + 2 < NT;
;         if (more2) ATT_ISSUE(t + 2, s2);
;         const int buf = s0i;
;         if (64 * t <= q0 + 32 * wid + 31) {
;             const LAS unsigned char* kb = lds + buf * AK_BYTES + r32 * AK_PITCH + hi * 16;
	v_mov_b32_e32 v64, v73
	v_mov_b32_e32 v72, v65
	v_pk_mul_f32 v[6:7], v[64:65], v[2:3]
	v_pk_mul_f32 v[2:3], v[72:73], v[2:3]
	v_pk_mul_f32 v[34:35], v[36:37], v[34:35]
	v_sub_f32_e32 v6, v7, v6
	v_add_f32_e32 v2, v2, v3
	v_add_f32_e32 v34, v34, v35
	v_cvt_pk_bf16_f32 v153, v38, v6
	v_cvt_pk_bf16_f32 v157, v34, v2
	v_lshlrev_b32_e32 v3, 16, v4
	v_lshlrev_b32_e32 v2, 16, v8
	v_mov_b32_e32 v6, v66
	v_mov_b32_e32 v7, v58
	v_pk_mul_f32 v[6:7], v[6:7], v[2:3]
	s_nop 0
	v_sub_f32_e32 v34, v7, v6
	v_mov_b32_e32 v6, v58
	v_mov_b32_e32 v7, v66
	v_pk_mul_f32 v[2:3], v[6:7], v[2:3]
	v_mov_b32_e32 v58, v67
	v_add_f32_e32 v35, v2, v3
	v_and_b32_e32 v3, 0xffff0000, v4
	v_and_b32_e32 v2, 0xffff0000, v8
	v_mov_b32_e32 v66, v59
	v_pk_mul_f32 v[6:7], v[58:59], v[2:3]
	v_pk_mul_f32 v[2:3], v[66:67], v[2:3]
	v_sub_f32_e32 v4, v7, v6
	v_add_f32_e32 v2, v2, v3
	v_cvt_pk_bf16_f32 v158, v35, v2
	v_lshlrev_b32_e32 v3, 16, v5
	v_lshlrev_b32_e32 v2, 16, v9
	v_mov_b32_e32 v6, v68
	v_mov_b32_e32 v7, v60
	v_pk_mul_f32 v[6:7], v[6:7], v[2:3]
	v_cvt_pk_bf16_f32 v154, v34, v4
	s_nop 0
	v_sub_f32_e32 v8, v7, v6
	v_mov_b32_e32 v6, v60
	v_mov_b32_e32 v7, v68
	v_pk_mul_f32 v[2:3], v[6:7], v[2:3]
	v_mov_b32_e32 v60, v69
	v_add_f32_e32 v6, v2, v3
	v_and_b32_e32 v3, 0xffff0000, v5
	v_and_b32_e32 v2, 0xffff0000, v9
	v_mov_b32_e32 v68, v61
	v_pk_mul_f32 v[4:5], v[60:61], v[2:3]
	v_pk_mul_f32 v[2:3], v[68:69], v[2:3]
	v_sub_f32_e32 v4, v5, v4
	v_add_f32_e32 v2, v2, v3
	v_cvt_pk_bf16_f32 v159, v6, v2
	v_mul_u32_u24_e32 v2, 0x190, v190
	v_add3_u32 v191, 0, v2, v0
	v_lshrrev_b32_e32 v0, 2, v188
	v_and_b32_e32 v2, 16, v188
	v_lshlrev_b32_e32 v3, 2, v188
	v_and_or_b32 v0, v0, 3, v192
	v_and_or_b32 v2, v3, 12, v2
	v_mul_u32_u24_e32 v0, 0x140, v0
	v_lshlrev_b32_e32 v2, 1, v2
	v_cvt_pk_bf16_f32 v155, v8, v4
	v_add3_u32 v193, s47, v0, v2
	v_mov_b32_e32 v0, v1
	v_mov_b32_e32 v2, v1
	v_mov_b32_e32 v3, v1
	v_mov_b32_e32 v4, v1
	v_mov_b32_e32 v5, v1
	v_mov_b32_e32 v6, v1
	v_mov_b32_e32 v7, v1
	v_mov_b32_e32 v8, v1
	v_mov_b32_e32 v9, v1
	v_mov_b64_e32 v[30:31], v[14:15]
	v_mov_b64_e32 v[46:47], v[14:15]
	v_mov_b64_e32 v[62:63], v[14:15]
	v_mov_b64_e32 v[78:79], v[14:15]
	v_mov_b64_e32 v[28:29], v[12:13]
	v_mov_b64_e32 v[26:27], v[10:11]
	v_mov_b64_e32 v[24:25], v[8:9]
	v_mov_b64_e32 v[22:23], v[6:7]
	v_mov_b64_e32 v[20:21], v[4:5]
	v_mov_b64_e32 v[18:19], v[2:3]
	v_mov_b64_e32 v[16:17], v[0:1]
	v_mov_b64_e32 v[44:45], v[12:13]
	v_mov_b64_e32 v[42:43], v[10:11]
	v_mov_b64_e32 v[40:41], v[8:9]
	v_mov_b64_e32 v[38:39], v[6:7]
	v_mov_b64_e32 v[36:37], v[4:5]
	v_mov_b64_e32 v[34:35], v[2:3]
	v_mov_b64_e32 v[32:33], v[0:1]
	v_mov_b64_e32 v[60:61], v[12:13]
	v_mov_b64_e32 v[58:59], v[10:11]
	v_mov_b64_e32 v[56:57], v[8:9]
	v_mov_b64_e32 v[54:55], v[6:7]
	v_mov_b64_e32 v[52:53], v[4:5]
	v_mov_b64_e32 v[50:51], v[2:3]
	v_mov_b64_e32 v[48:49], v[0:1]
	v_mov_b64_e32 v[76:77], v[12:13]
	v_mov_b64_e32 v[74:75], v[10:11]
	v_mov_b64_e32 v[72:73], v[8:9]
	v_mov_b64_e32 v[70:71], v[6:7]
	v_mov_b64_e32 v[68:69], v[4:5]
	v_mov_b64_e32 v[66:67], v[2:3]
	v_mov_b64_e32 v[64:65], v[0:1]
.LBB0_647:
	s_mov_b32 s27, s6
	s_add_i32 s6, s26, 2
	s_cmp_ge_u32 s6, s54
	s_cselect_b64 s[6:7], -1, 0
	s_add_i32 s16, s26, 1
	s_cmp_ge_u32 s16, s54
	s_cbranch_scc1 .LBB0_651
	s_mul_i32 s16, s53, s19
	s_add_i32 s16, s50, s16
	s_mov_b32 s17, m0
	s_mov_b32 m0, s16
	s_nop 0
	global_load_lds_dwordx4 v[178:179], off
	s_mov_b32 m0, s17
	s_mul_i32 s16, s53, s20
	s_add_i32 s16, s51, s16
	s_mov_b32 s17, m0
	s_mov_b32 m0, s16
	s_nop 0
	global_load_lds_dwordx4 v[176:177], off
	s_mov_b32 m0, s17
	s_mul_i32 s16, s53, s24
	s_add_i32 s16, s52, s16
	s_mov_b32 s17, m0
	s_mov_b32 m0, s16
	s_nop 0
	global_load_lds_dwordx4 v[174:175], off
	s_mov_b32 m0, s17
	s_and_b64 vcc, exec, s[6:7]
	s_cbranch_vccnz .LBB0_651
	s_mul_i32 s16, s57, s58
	s_add_i32 s16, s28, s16
	s_mov_b32 s17, m0
	s_mov_b32 m0, s16
	s_nop 0
	global_load_lds_dwordx4 v[184:185], off
	s_mov_b32 m0, s17
	s_mul_i32 s16, s57, s59
	s_add_i32 s16, s29, s16
	s_mov_b32 s17, m0
	s_mov_b32 m0, s16
	s_nop 0
	global_load_lds_dwordx4 v[182:183], off
	s_mov_b32 m0, s17
	s_mul_i32 s16, s57, s18
	s_add_i32 s16, s31, s16
	s_mov_b32 s17, m0
	s_mov_b32 m0, s16
	s_nop 0
	global_load_lds_dwordx4 v[180:181], off
	s_mov_b32 m0, s17
	s_cmp_gt_i32 s21, s55
	s_cbranch_scc0 .LBB0_652

; __device__ __forceinline__ void attn_unit(int bh, int qb, const bf16_t* Q, const bf16_t* KN, const bf16_t* KPE, const bf16_t* VT, const float* COS, const float* SIN, bf16_t* O, LAS unsigned char* lds, int wv) {
;     ...
;             float mx = s0[0];
; #pragma unroll
;             for (int r = 1; r < 16; ++r) mx = fmaxf(mx, s0[r]);
; #pragma unroll
;             for (int r = 0; r < 16; ++r) mx = fmaxf(mx, s1[r]);
;             mx = fmaxf(mx, __shfl_xor(mx, 32));
;             const bool grow = mx > m_run + 6.0f;
;             if (__builtin_amdgcn_ballot_w64(grow) != 0ull) {
;                 const float m_new = grow ? mx : m_run, alpha = __builtin_amdgcn_exp2f(m_run - m_new); m_run = m_new; l_run *= alpha;
; #pragma unroll
;                 for (int d0 = 0; d0 < 4; ++d0)
; #pragma unroll
;                     for (int r = 0; r < 16; ++r) o[d0][r] *= alpha;
;             }
;     ...
;         if (more2) asm volatile("s_waitcnt vmcnt(6) lgkmcnt(0)\n\ts_barrier" ::: "memory");
;         else asm volatile("s_waitcnt vmcnt(0) lgkmcnt(0)\n\ts_barrier" ::: "memory");
.LBB0_654:
	s_cmp_lt_u32 s49, 4
	s_cbranch_scc1 .Latt_nomid
	s_and_b64 vcc, exec, s[6:7]
	s_cbranch_vccnz .Latt_mid0
	s_waitcnt vmcnt(3) lgkmcnt(0)
	s_barrier
	s_branch .Latt_nomid
.Latt_mid0:
	s_waitcnt vmcnt(0) lgkmcnt(0)
	s_barrier
.Latt_nomid:
	s_nop 8
	v_max_f32_e32 v0, v81, v81
	v_max_f32_e32 v2, v80, v80
	v_max_f32_e32 v0, v2, v0
	v_max3_f32 v0, v0, v82, v83
	v_max3_f32 v0, v0, v84, v85
	v_max3_f32 v0, v0, v86, v87
	v_max3_f32 v0, v0, v88, v89
	v_max3_f32 v0, v0, v90, v91
	v_max3_f32 v0, v0, v92, v93
	v_max3_f32 v0, v0, v94, v95
	v_max3_f32 v0, v0, v96, v97
	v_max3_f32 v0, v0, v98, v99
	v_max3_f32 v0, v0, v100, v101
	v_max3_f32 v0, v0, v102, v103
	v_and_b32_e32 v3, 64, v186
	v_max3_f32 v0, v0, v104, v105
	v_xor_b32_e32 v2, 32, v186
	v_add_u32_e32 v3, 64, v3
	v_max3_f32 v0, v0, v106, v107
	v_cmp_lt_i32_e32 vcc, v2, v3
	v_max3_f32 v0, v0, v108, v109
	v_max3_f32 v0, v0, v110, v111
	v_cndmask_b32_e32 v2, v186, v2, vcc
	v_lshlrev_b32_e32 v2, 2, v2
	ds_bpermute_b32 v2, v2, v0
	s_waitcnt lgkmcnt(0)
	v_max_f32_e32 v2, v2, v2
	v_max_f32_e32 v0, v0, v2
	v_add_f32_e32 v2, 0x40c00000, v195
	v_cmp_gt_f32_e32 vcc, v0, v2
	s_cbranch_vccz .LBB0_656
	s_nop 0
	v_cndmask_b32_e32 v2, v195, v0, vcc
	v_sub_f32_e32 v0, v195, v2
	v_exp_f32_e32 v0, v0
	v_mov_b32_e32 v195, v2
	v_pk_mul_f32 v[78:79], v[78:79], v[0:1] op_sel_hi:[1,0]
	v_pk_mul_f32 v[76:77], v[76:77], v[0:1] op_sel_hi:[1,0]
	v_pk_mul_f32 v[74:75], v[74:75], v[0:1] op_sel_hi:[1,0]
	v_pk_mul_f32 v[72:73], v[72:73], v[0:1] op_sel_hi:[1,0]
	v_pk_mul_f32 v[70:71], v[70:71], v[0:1] op_sel_hi:[1,0]
	v_pk_mul_f32 v[68:69], v[68:69], v[0:1] op_sel_hi:[1,0]
	v_pk_mul_f32 v[66:67], v[66:67], v[0:1] op_sel_hi:[1,0]
	v_pk_mul_f32 v[64:65], v[64:65], v[0:1] op_sel_hi:[1,0]
	v_pk_mul_f32 v[62:63], v[62:63], v[0:1] op_sel_hi:[1,0]
	v_pk_mul_f32 v[60:61], v[60:61], v[0:1] op_sel_hi:[1,0]
	v_pk_mul_f32 v[58:59], v[58:59], v[0:1] op_sel_hi:[1,0]
	v_pk_mul_f32 v[56:57], v[56:57], v[0:1] op_sel_hi:[1,0]
	v_pk_mul_f32 v[54:55], v[54:55], v[0:1] op_sel_hi:[1,0]
	v_pk_mul_f32 v[52:53], v[52:53], v[0:1] op_sel_hi:[1,0]
	v_pk_mul_f32 v[50:51], v[50:51], v[0:1] op_sel_hi:[1,0]
	v_pk_mul_f32 v[48:49], v[48:49], v[0:1] op_sel_hi:[1,0]
	v_pk_mul_f32 v[46:47], v[46:47], v[0:1] op_sel_hi:[1,0]
	v_pk_mul_f32 v[44:45], v[44:45], v[0:1] op_sel_hi:[1,0]
	v_pk_mul_f32 v[42:43], v[42:43], v[0:1] op_sel_hi:[1,0]
	v_pk_mul_f32 v[40:41], v[40:41], v[0:1] op_sel_hi:[1,0]
	v_pk_mul_f32 v[38:39], v[38:39], v[0:1] op_sel_hi:[1,0]
	v_pk_mul_f32 v[36:37], v[36:37], v[0:1] op_sel_hi:[1,0]
	v_pk_mul_f32 v[34:35], v[34:35], v[0:1] op_sel_hi:[1,0]
	v_pk_mul_f32 v[32:33], v[32:33], v[0:1] op_sel_hi:[1,0]
	v_pk_mul_f32 v[30:31], v[30:31], v[0:1] op_sel_hi:[1,0]
	v_pk_mul_f32 v[28:29], v[28:29], v[0:1] op_sel_hi:[1,0]
	v_pk_mul_f32 v[26:27], v[26:27], v[0:1] op_sel_hi:[1,0]
	v_pk_mul_f32 v[24:25], v[24:25], v[0:1] op_sel_hi:[1,0]
	v_pk_mul_f32 v[22:23], v[22:23], v[0:1] op_sel_hi:[1,0]
	v_pk_mul_f32 v[20:21], v[20:21], v[0:1] op_sel_hi:[1,0]
	v_pk_mul_f32 v[18:19], v[18:19], v[0:1] op_sel_hi:[1,0]
	v_pk_mul_f32 v[16:17], v[16:17], v[0:1] op_sel_hi:[1,0]
	v_mul_f32_e32 v194, v194, v0
; __device__ __forceinline__ unsigned cvt_pk_bf16(float lo, float hi) { unsigned r; asm("v_cvt_pk_bf16_f32 %0, %1, %2" : "=v"(r) : "v"(lo), "v"(hi)); return r; }
; #define LAS __attribute__((address_space(3)))
; __device__ __forceinline__ void attn_unit(int bh, int qb, const bf16_t* Q, const bf16_t* KN, const bf16_t* KPE, const bf16_t* VT, const float* COS, const float* SIN, bf16_t* O, LAS unsigned char* lds, int wv) {
;     ...
;             float ls = 0.f;
; #pragma unroll
;             for (int r = 0; r < 16; ++r) { s0[r] = __builtin_amdgcn_exp2f(s0[r] - m_run); s1[r] = __builtin_amdgcn_exp2f(s1[r] - m_run); ls += s0[r] + s1[r]; }
;             l_run += ls;
;             bf16x8 pf[4];
;             { u32x4 w;
;               w.x = cvt_pk_bf16(s0[0], s0[1]); w.y = cvt_pk_bf16(s0[2], s0[3]); w.z = cvt_pk_bf16(s0[4], s0[5]); w.w = cvt_pk_bf16(s0[6], s0[7]); pf[0] = __builtin_bit_cast(bf16x8, w);
;               w.x = cvt_pk_bf16(s0[8], s0[9]); w.y = cvt_pk_bf16(s0[10], s0[11]); w.z = cvt_pk_bf16(s0[12], s0[13]); w.w = cvt_pk_bf16(s0[14], s0[15]); pf[1] = __builtin_bit_cast(bf16x8, w);
;               w.x = cvt_pk_bf16(s1[0], s1[1]); w.y = cvt_pk_bf16(s1[2], s1[3]); w.z = cvt_pk_bf16(s1[4], s1[5]); w.w = cvt_pk_bf16(s1[6], s1[7]); pf[2] = __builtin_bit_cast(bf16x8, w);
;               w.x = cvt_pk_bf16(s1[8], s1[9]); w.y = cvt_pk_bf16(s1[10], s1[11]); w.z = cvt_pk_bf16(s1[12], s1[13]); w.w = cvt_pk_bf16(s1[14], s1[15]); pf[3] = __builtin_bit_cast(bf16x8, w); }
;             const LAS unsigned char* vb = lds + 3 * AK_BYTES + buf * AV_BYTES + (4 * hi + ((lane & 15) >> 2)) * AV_PITCH + (16 * ((lane >> 4) & 1) + 4 * (lane & 3)) * 2;
; #pragma unroll
;             for (int d0 = 0; d0 < 4; ++d0)
; #pragma unroll
;                 for (int ks = 0; ks < 4; ++ks) {
;                     const att_v4i16 lo4 = __builtin_amdgcn_ds_read_tr16_b64_v4i16((LAS att_v4i16*)(vb + ks * 16 * AV_PITCH + d0 * 64));
;                     const att_v4i16 hi4 = __builtin_amdgcn_ds_read_tr16_b64_v4i16((LAS att_v4i16*)(vb + (ks * 16 + 8) * AV_PITCH + d0 * 64));
;                     const bf16x8 vf = {lo4[0], lo4[1], lo4[2], lo4[3], hi4[0], hi4[1], hi4[2], hi4[3]};
;                     o[d0] = __builtin_amdgcn_mfma_f32_32x32x16_bf16(vf, pf[ks], o[d0], 0, 0, 0); }
.LBB0_656:
	v_sub_f32_e32 v2, v96, v195
	v_sub_f32_e32 v0, v80, v195
	v_exp_f32_e32 v246, v2
	v_sub_f32_e32 v2, v81, v195
	v_sub_f32_e32 v80, v107, v195
	v_exp_f32_e32 v247, v2
	v_sub_f32_e32 v2, v97, v195
	v_exp_f32_e32 v236, v80
	v_sub_f32_e32 v80, v92, v195
	v_exp_f32_e32 v248, v2
	v_sub_f32_e32 v2, v82, v195
	v_exp_f32_e32 v239, v80
	v_sub_f32_e32 v80, v108, v195
	v_exp_f32_e32 v249, v2
	v_sub_f32_e32 v2, v98, v195
	v_exp_f32_e32 v241, v80
	v_sub_f32_e32 v80, v93, v195
	v_exp_f32_e32 v250, v2
	v_sub_f32_e32 v2, v83, v195
	v_exp_f32_e32 v238, v80
	v_sub_f32_e32 v80, v109, v195
	v_exp_f32_e32 v251, v2
	v_sub_f32_e32 v2, v99, v195
	v_exp_f32_e32 v240, v80
	v_sub_f32_e32 v80, v94, v195
	s_mul_i32 s16, s27, 0x5000
	v_exp_f32_e32 v252, v2
	v_sub_f32_e32 v2, v84, v195
	v_sub_f32_e32 v6, v86, v195
	v_sub_f32_e32 v10, v88, v195
	v_sub_f32_e32 v14, v90, v195
	v_exp_f32_e32 v243, v80
	v_sub_f32_e32 v80, v110, v195
	v_add_u32_e32 v110, s16, v193
	v_exp_f32_e32 v3, v2
	v_sub_f32_e32 v2, v100, v195
	v_sub_f32_e32 v4, v101, v195
	v_exp_f32_e32 v7, v6
	v_sub_f32_e32 v6, v102, v195
	v_sub_f32_e32 v8, v103, v195
	v_exp_f32_e32 v11, v10
	v_sub_f32_e32 v10, v104, v195
	v_sub_f32_e32 v12, v105, v195
	v_exp_f32_e32 v15, v14
	v_sub_f32_e32 v14, v106, v195
	v_exp_f32_e32 v245, v80
	v_sub_f32_e32 v80, v95, v195
	ds_read_b64_tr_b16 v[94:95], v110
	ds_read_b64_tr_b16 v[96:97], v110 offset:2560
	ds_read_b64_tr_b16 v[98:99], v110 offset:5120
	ds_read_b64_tr_b16 v[100:101], v110 offset:7680
	ds_read_b64_tr_b16 v[102:103], v110 offset:64
	ds_read_b64_tr_b16 v[106:107], v110 offset:128
	ds_read_b64_tr_b16 v[196:197], v110 offset:192
	ds_read_b64_tr_b16 v[104:105], v110 offset:2624
	ds_read_b64_tr_b16 v[108:109], v110 offset:2688
	ds_read_b64_tr_b16 v[198:199], v110 offset:2752
	v_exp_f32_e32 v5, v2
	v_sub_f32_e32 v2, v85, v195
	v_exp_f32_e32 v9, v6
	v_sub_f32_e32 v6, v87, v195
	v_exp_f32_e32 v242, v80
	v_sub_f32_e32 v80, v111, v195
	v_exp_f32_e32 v0, v0
	v_exp_f32_e32 v2, v2
	v_exp_f32_e32 v6, v6
	v_exp_f32_e32 v244, v80
	v_cvt_pk_bf16_f32 v80, v0, v247
	v_cvt_pk_bf16_f32 v81, v249, v251
	v_cvt_pk_bf16_f32 v82, v3, v2
	v_cvt_pk_bf16_f32 v83, v7, v6
	ds_read_b64_tr_b16 v[200:201], v110 offset:5184
	ds_read_b64_tr_b16 v[204:205], v110 offset:5248
	ds_read_b64_tr_b16 v[208:209], v110 offset:5312
	ds_read_b64_tr_b16 v[202:203], v110 offset:7744
	ds_read_b64_tr_b16 v[206:207], v110 offset:7808
	ds_read_b64_tr_b16 v[210:211], v110 offset:7872
	s_waitcnt lgkmcnt(14)
	v_mfma_f32_32x32x16_bf16 v[64:79], v[94:97], v[80:83], v[64:79]
	v_exp_f32_e32 v13, v10
	v_sub_f32_e32 v10, v89, v195
	v_exp_f32_e32 v237, v14
	v_sub_f32_e32 v14, v91, v195
	v_exp_f32_e32 v10, v10
	v_exp_f32_e32 v14, v14
	v_cvt_pk_bf16_f32 v84, v11, v10
	s_waitcnt lgkmcnt(8)
	v_mfma_f32_32x32x16_bf16 v[48:63], v[102:105], v[80:83], v[48:63]
	v_cvt_pk_bf16_f32 v85, v15, v14
	v_cvt_pk_bf16_f32 v86, v239, v238
	v_cvt_pk_bf16_f32 v87, v243, v242
	v_exp_f32_e32 v4, v4
	v_add_f32_e32 v0, v0, v246
	v_add_f32_e32 v0, 0, v0
	v_exp_f32_e32 v8, v8
	s_waitcnt lgkmcnt(7)
	v_mfma_f32_32x32x16_bf16 v[32:47], v[106:109], v[80:83], v[32:47]
	v_cvt_pk_bf16_f32 v88, v246, v248
	v_cvt_pk_bf16_f32 v89, v250, v252
	v_cvt_pk_bf16_f32 v90, v5, v4
	v_cvt_pk_bf16_f32 v91, v9, v8
	v_exp_f32_e32 v12, v12
	v_pk_add_f32 v[2:3], v[2:3], v[4:5]
	v_pk_add_f32 v[4:5], v[6:7], v[8:9]
	s_waitcnt lgkmcnt(6)
	v_mfma_f32_32x32x16_bf16 v[16:31], v[196:199], v[80:83], v[16:31]
	v_add_f32_e32 v80, v247, v248
	v_add_f32_e32 v81, v249, v250
	v_add_f32_e32 v0, v80, v0
	v_add_f32_e32 v82, v251, v252
	v_add_f32_e32 v0, v81, v0
	v_add_f32_e32 v0, v82, v0
	v_add_f32_e32 v0, v3, v0
	v_mfma_f32_32x32x16_bf16 v[64:79], v[98:101], v[84:87], v[64:79]
	ds_read_b64_tr_b16 v[96:97], v110 offset:10240
	ds_read_b64_tr_b16 v[98:99], v110 offset:12800
	ds_read_b64_tr_b16 v[212:213], v110 offset:15360
	ds_read_b64_tr_b16 v[214:215], v110 offset:17920
	ds_read_b64_tr_b16 v[216:217], v110 offset:10304
	ds_read_b64_tr_b16 v[220:221], v110 offset:10368
	ds_read_b64_tr_b16 v[224:225], v110 offset:10432
	ds_read_b64_tr_b16 v[218:219], v110 offset:12864
	ds_read_b64_tr_b16 v[222:223], v110 offset:12928
	ds_read_b64_tr_b16 v[226:227], v110 offset:12992
	v_add_f32_e32 v0, v2, v0
	v_add_f32_e32 v0, v5, v0
	v_pk_add_f32 v[6:7], v[10:11], v[12:13]
	v_add_f32_e32 v0, v4, v0
	v_add_f32_e32 v0, v7, v0
	v_cvt_pk_bf16_f32 v92, v13, v12
	s_waitcnt lgkmcnt(12)
	v_mfma_f32_32x32x16_bf16 v[48:63], v[200:203], v[84:87], v[48:63]
	v_cvt_pk_bf16_f32 v93, v237, v236
	v_cvt_pk_bf16_f32 v94, v241, v240
	v_cvt_pk_bf16_f32 v95, v245, v244
	v_add_f32_e64 v8, v14, v236
	v_add_f32_e64 v9, v15, v237
	v_add_f32_e32 v0, v6, v0
	v_add_f32_e32 v0, v9, v0
	v_add_f32_e64 v10, v238, v240
	v_add_f32_e64 v11, v239, v241
	s_waitcnt lgkmcnt(11)
	v_mfma_f32_32x32x16_bf16 v[32:47], v[204:207], v[84:87], v[32:47]
	v_add_f32_e32 v0, v8, v0
	v_add_f32_e32 v0, v11, v0
	v_add_f32_e64 v12, v242, v244
	v_add_f32_e64 v13, v243, v245
	v_add_f32_e32 v0, v10, v0
	v_add_f32_e32 v0, v13, v0
	v_add_f32_e32 v0, v12, v0
	v_add_f32_e32 v194, v194, v0
	s_waitcnt lgkmcnt(10)
	v_mfma_f32_32x32x16_bf16 v[16:31], v[208:211], v[84:87], v[16:31]
	s_waitcnt lgkmcnt(8)
	v_mfma_f32_32x32x16_bf16 v[64:79], v[96:99], v[88:91], v[64:79]
	ds_read_b64_tr_b16 v[96:97], v110 offset:15424
	ds_read_b64_tr_b16 v[228:229], v110 offset:15488
	ds_read_b64_tr_b16 v[232:233], v110 offset:15552
	ds_read_b64_tr_b16 v[98:99], v110 offset:17984
	ds_read_b64_tr_b16 v[230:231], v110 offset:18048
	ds_read_b64_tr_b16 v[234:235], v110 offset:18112
	s_waitcnt lgkmcnt(8)
	v_mfma_f32_32x32x16_bf16 v[48:63], v[216:219], v[88:91], v[48:63]
	s_waitcnt lgkmcnt(7)
	v_mfma_f32_32x32x16_bf16 v[32:47], v[220:223], v[88:91], v[32:47]
	s_waitcnt lgkmcnt(6)
	v_mfma_f32_32x32x16_bf16 v[16:31], v[224:227], v[88:91], v[16:31]
	v_mfma_f32_32x32x16_bf16 v[64:79], v[212:215], v[92:95], v[64:79]
	s_waitcnt lgkmcnt(2)
	v_mfma_f32_32x32x16_bf16 v[48:63], v[96:99], v[92:95], v[48:63]
	s_waitcnt lgkmcnt(1)
	v_mfma_f32_32x32x16_bf16 v[32:47], v[228:231], v[92:95], v[32:47]
	s_waitcnt lgkmcnt(0)
	v_mfma_f32_32x32x16_bf16 v[16:31], v[232:235], v[92:95], v[16:31]
	s_cmp_lt_u32 s49, 4
	s_cbranch_scc0 .LBB0_659
	s_mov_b64 s[16:17], -1
	s_and_b64 vcc, exec, s[6:7]
	s_cbranch_vccnz .LBB0_650

; __device__ __forceinline__ void attn_unit(int bh, int qb, const bf16_t* Q, const bf16_t* KN, const bf16_t* KPE, const bf16_t* VT, const float* COS, const float* SIN, bf16_t* O, LAS unsigned char* lds, int wv) {
;     ...
;         { const int tmp_ = s0i; s0i = s1i; s1i = s2; s2 = tmp_; }
;         if (more2) asm volatile("s_waitcnt vmcnt(6) lgkmcnt(0)\n\ts_barrier" ::: "memory");
;         else asm volatile("s_waitcnt vmcnt(0) lgkmcnt(0)\n\ts_barrier" ::: "memory");
.LBB0_658:
	s_waitcnt vmcnt(3) lgkmcnt(0)
	s_barrier
